# combined: dilated and natten table rebuild only on head change, natten per-task barriers skipped, hyena next batch-pair v rows prefetched
# speedup vs baseline: 1.0090x; 1.0090x over previous
; __device__ __forceinline__ uint4 ntld_u4(const void* p) { const ntu4_t v = __builtin_nontemporal_load((const ntu4_t*)p); return make_uint4(v.x, v.y, v.z, v.w); }
; __device__ __forceinline__ float bf2f(bf16_t b) { return __uint_as_float(((unsigned)b) << 16); }
; __device__ __forceinline__ void lds_barrier() { asm volatile("s_waitcnt lgkmcnt(0)\n\ts_barrier" ::: "memory"); }
; __device__ __forceinline__ Raw8 load_raw8(const bf16_t* __restrict__ row, int n0) {
;     Raw8 r; r.body = ntld_u4(row + n0); r.eL = row[n0 > 0 ? n0 - 1 : 0]; r.eR = row[n0 + 8 < SEQ ? n0 + 8 : SEQ - 1]; return r; }
; __device__ __forceinline__ void sconv8(const Raw8& r, int n0, float w0, float w1, float w2, float b, float (&out)[8]) {
;     float a[10]; a[0] = n0 > 0 ? bf2f(r.eL) : 0.f; a[9] = n0 + 8 < SEQ ? bf2f(r.eR) : 0.f;
;     a[1] = __uint_as_float(r.body.x << 16); a[2] = __uint_as_float(r.body.x & 0xffff0000u); a[3] = __uint_as_float(r.body.y << 16); a[4] = __uint_as_float(r.body.y & 0xffff0000u);
;     a[5] = __uint_as_float(r.body.z << 16); a[6] = __uint_as_float(r.body.z & 0xffff0000u); a[7] = __uint_as_float(r.body.w << 16); a[8] = __uint_as_float(r.body.w & 0xffff0000u);
; #pragma unroll
;     for (int k = 0; k < 8; ++k) out[k] = w0 * a[k] + w1 * a[k + 1] + w2 * a[k + 2] + b;
; __device__ void ph_hyena_fft(const Params& P, int j, const bf16_t* __restrict__ projAT, const float* __restrict__ kf, bf16_t* __restrict__ yaT, unsigned char* lds_raw) {
;     ...
;         for (int bp = 0; bp < 4; ++bp) {
;             const size_t o0 = (size_t)(2 * bp) * SEQ, o1 = o0 + SEQ;
;             float va[8], vb[8];
;             { const Raw8 r0 = load_raw8(vrow + o0, n0), r1 = load_raw8(vrow + o1, n0); sconv8(r0, n0, wv0, wv1, wv2, bv, va); sconv8(r1, n0, wv0, wv1, wv2, bv, vb); }
; #pragma unroll
;             for (int k = 0; k < 8; ++k) { buf[ph0 + k] = mkv2(va[k], vb[k]); buf[ph0 + 4352 + k] = mkv2(0.f, 0.f); }
;             const Raw8 xa0 = load_raw8(x1row + o0, n0), xa1 = load_raw8(x1row + o1, n0);
;             lds_barrier();
;             fft_conv(buf, spec1);
.LBB0_346:
	s_lshl_b32 s11, s53, 13
	s_or_b32 s10, s11, 0x1000
	s_lshl_b32 s0, s53, 14
	s_lshl_b32 s1, s10, 1
	s_cmp_lg_u32 s53, 0
	s_cbranch_scc1 .Lhy_skipv
	s_add_u32 s6, s47, s0
	s_addc_u32 s7, s58, 0
	v_lshl_add_u64 v[0:1], s[6:7], 0, v[16:17]
	global_load_ushort v184, v146, s[6:7] offset:-2
	global_load_dwordx4 v[176:179], v[0:1], off nt
	v_lshl_add_u64 v[0:1], s[6:7], 0, v[22:23]
	s_add_u32 s6, s47, s1
	s_addc_u32 s7, s58, 0
	v_lshl_add_u64 v[2:3], s[6:7], 0, v[22:23]
	global_load_ushort v185, v146, s[6:7] offset:-2
	global_load_ushort v186, v[2:3], off offset:16
	global_load_ushort v187, v[0:1], off offset:16
	v_lshl_add_u64 v[0:1], s[6:7], 0, v[16:17]
	global_load_dwordx4 v[180:183], v[0:1], off nt
.Lhy_skipv:
	s_add_u32 s6, s59, s0
	s_addc_u32 s7, s60, 0
	s_add_u32 s0, s59, s1
	global_load_ushort v143, v146, s[6:7] offset:-2
	v_lshl_add_u64 v[0:1], s[6:7], 0, v[16:17]
	s_addc_u32 s1, s60, 0
	v_lshl_add_u64 v[2:3], s[6:7], 0, v[22:23]
	global_load_dwordx4 v[4:7], v[0:1], off nt
	global_load_ushort v144, v[2:3], off offset:16
	v_lshl_add_u64 v[0:1], s[0:1], 0, v[16:17]
	global_load_ushort v139, v146, s[0:1] offset:-2
	v_lshl_add_u64 v[64:65], s[0:1], 0, v[22:23]
	global_load_dwordx4 v[0:3], v[0:1], off nt
	s_nop 0
	global_load_ushort v141, v[64:65], off offset:16
	v_add_u32_e32 v142, 0x8800, v145
	v_add_u32_e32 v138, 0x8810, v145
	v_add_u32_e32 v140, 0x8820, v145
	v_add_u32_e32 v137, 0x8830, v145
	s_mov_b64 s[6:7], -1
	s_mov_b32 s0, 0
	s_waitcnt vmcnt(11)
	v_lshlrev_b32_e32 v64, 16, v184
	s_waitcnt vmcnt(10)
	v_and_b32_e32 v65, 0xffff0000, v179
	v_lshlrev_b32_e32 v62, 16, v176
	v_lshlrev_b32_e32 v67, 16, v178
	v_lshlrev_b32_e32 v63, 16, v177
	v_and_b32_e32 v9, 0xffff0000, v177
	v_and_b32_e32 v8, 0xffff0000, v176
	v_and_b32_e32 v69, 16, v179
	v_lshlrev_b32_e32 v11, 16, v179
	v_cndmask_b32_e64 v71, 0, v64, s[42:43]
	v_mov_b32_e32 v70, v63
	v_pk_mul_f32 v[74:75], v[60:61], v[8:9]
	v_mov_b32_e32 v76, v67
	v_mov_b32_e32 v77, v11
	v_and_b32_e32 v68, 0xffff0000, v178
	v_mov_b32_e32 v66, v63
	v_mov_b32_e32 v72, v62
	v_mov_b32_e32 v73, v8
	s_waitcnt vmcnt(9)
	v_lshlrev_b32_e32 v79, 16, v185
	v_pk_mul_f32 v[70:71], v[24:25], v[70:71]
	v_pk_fma_f32 v[62:63], v[58:59], v[62:63], v[74:75]
	v_pk_mul_f32 v[74:75], v[60:61], v[76:77]
	s_waitcnt vmcnt(8)
	v_lshlrev_b32_e32 v76, 16, v186
	s_waitcnt vmcnt(6)
	v_lshlrev_b32_e32 v80, 16, v180
	v_and_b32_e32 v84, 0xffff0000, v180
	v_lshlrev_b32_e32 v12, 16, v181
	v_mov_b32_e32 v10, v68
	v_mov_b32_e32 v64, v68
	v_pk_mov_b32 v[68:69], v[8:9], v[68:69] op_sel:[1,0]
	v_lshlrev_b32_e32 v81, 16, v187
	v_cndmask_b32_e64 v77, 0, v79, s[42:43]
	v_pk_fma_f32 v[70:71], v[24:25], v[72:73], v[70:71] op_sel:[0,0,1] op_sel_hi:[1,1,0]
	v_pk_fma_f32 v[62:63], v[26:27], v[66:67], v[62:63]
	v_mov_b32_e32 v66, v65
	v_cndmask_b32_e64 v73, 0, v76, s[44:45]
	v_mov_b32_e32 v76, v12
	v_and_b32_e32 v85, 0xffff0000, v181
	v_cndmask_b32_e64 v79, 0, v81, s[44:45]
	v_pk_fma_f32 v[68:69], v[58:59], v[68:69], v[74:75]
	v_mov_b32_e32 v81, v84
	v_pk_fma_f32 v[8:9], v[26:27], v[8:9], v[70:71]
	v_pk_mul_f32 v[66:67], v[24:25], v[66:67]
	v_pk_mul_f32 v[70:71], v[24:25], v[76:77]
	v_mov_b32_e32 v78, v11
	v_pk_mul_f32 v[74:75], v[60:61], v[84:85]
	v_pk_fma_f32 v[68:69], v[26:27], v[64:65], v[68:69]
	v_pk_fma_f32 v[10:11], v[24:25], v[10:11], v[66:67] op_sel:[0,0,1] op_sel_hi:[1,1,0]
	v_pk_fma_f32 v[66:67], v[24:25], v[80:81], v[70:71] op_sel:[0,0,1] op_sel_hi:[1,1,0]
	v_mov_b32_e32 v81, v12
	v_lshlrev_b32_e32 v13, 16, v182
	v_pk_add_f32 v[64:65], v[28:29], v[8:9]
	v_pk_add_f32 v[8:9], v[28:29], v[68:69]
	v_pk_fma_f32 v[68:69], v[58:59], v[80:81], v[74:75]
	v_lshlrev_b32_e32 v83, 16, v183
	v_and_b32_e32 v15, 0xffff0000, v183
	v_pk_fma_f32 v[68:69], v[26:27], v[12:13], v[68:69]
	v_and_b32_e32 v14, 0xffff0000, v182
	v_mov_b32_e32 v82, v13
	v_pk_add_f32 v[70:71], v[28:29], v[68:69]
	v_pk_mov_b32 v[68:69], v[84:85], v[14:15] op_sel:[1,0]
	v_pk_mul_f32 v[12:13], v[60:61], v[82:83]
	v_pk_fma_f32 v[66:67], v[26:27], v[84:85], v[66:67]
	v_pk_fma_f32 v[12:13], v[58:59], v[68:69], v[12:13]
	v_pk_add_f32 v[62:63], v[28:29], v[62:63]
	v_pk_fma_f32 v[12:13], v[26:27], v[14:15], v[12:13]
	v_pk_mul_f32 v[14:15], v[60:61], v[14:15]
	v_pk_add_f32 v[66:67], v[28:29], v[66:67]
	v_pk_fma_f32 v[14:15], v[58:59], v[82:83], v[14:15]
	v_mov_b32_e32 v72, v83
	v_pk_fma_f32 v[10:11], v[26:27], v[78:79], v[10:11]
	v_pk_fma_f32 v[14:15], v[26:27], v[72:73], v[14:15]
	v_mov_b32_e32 v68, v64
	v_mov_b32_e32 v69, v66
	v_mov_b32_e32 v72, v62
	v_mov_b32_e32 v73, v70
	v_pk_add_f32 v[10:11], v[28:29], v[10:11]
	v_pk_add_f32 v[12:13], v[28:29], v[12:13]
	v_pk_add_f32 v[14:15], v[28:29], v[14:15]
	ds_write2_b64 v145, v[68:69], v[72:73] offset1:1
	v_mov_b64_e32 v[68:69], s[48:49]
	v_mov_b64_e32 v[72:73], s[50:51]
	v_mov_b32_e32 v74, v65
	v_mov_b32_e32 v75, v67
	v_mov_b32_e32 v76, v63
	v_mov_b32_e32 v77, v71
	ds_write2_b64 v142, v[68:69], v[72:73] offset1:1
	ds_write2_b64 v145, v[74:75], v[76:77] offset0:2 offset1:3
	ds_write2_b64 v138, v[68:69], v[72:73] offset1:1
	v_mov_b32_e32 v74, v8
	v_mov_b32_e32 v75, v12
	v_mov_b32_e32 v76, v10
	v_mov_b32_e32 v77, v14
	ds_write2_b64 v145, v[74:75], v[76:77] offset0:4 offset1:5
	ds_write2_b64 v140, v[68:69], v[72:73] offset1:1
	v_mov_b32_e32 v74, v9
	v_mov_b32_e32 v75, v13
	v_mov_b32_e32 v76, v11
	v_mov_b32_e32 v77, v15
	ds_write2_b64 v145, v[74:75], v[76:77] offset0:6 offset1:7
	ds_write2_b64 v137, v[68:69], v[72:73] offset1:1
	s_waitcnt lgkmcnt(0)
	s_barrier
	v_mov_b32_e32 v68, v195

; #define LAS __attribute__((address_space(3)))
; __device__ __forceinline__ cf twc(cf ws, int k16) { if (k16 == 0) return ws; if (k16 == 4) return cf{ws.y, -ws.x}; return cmul(ws, cf{c16(k16), -s16(k16)}); }
; template <int LR> __device__ __forceinline__ void dif_reg(cf (&x)[1 << LR], cf w) {
;     constexpr int R = 1 << LR; cf ws = w;
; #pragma unroll
;     for (int s = 0; s < LR; ++s) { const int half = R >> (s + 1);
; #pragma unroll
;         for (int m0 = 0; m0 < R; m0 += 2 * half)
; #pragma unroll
;             for (int mm = 0; mm < half; ++mm) { const int ia = m0 + mm, ib = ia + half; const cf a = x[ia], b = x[ib];
;                 x[ia] = cf{a.x + b.x, a.y + b.y}; const cf d{a.x - b.x, a.y - b.y};
;                 x[ib] = cmul(d, twc(ws, (mm << s) * (16 / R))); }
;         ws = cmul(ws, ws); }
; }
; template <int LR, bool INV> __device__ __forceinline__ void fft_pass(ldsf2 buf, int base, int stride, int twi) {
;     constexpr int R = 1 << LR; cf x[R];
;     const v2f wv = ((ldsf2)((LAS unsigned char*)buf + 139264))[twi];
; #pragma unroll
;     for (int m = 0; m < R; ++m) { const v2f v = buf[base + m * stride]; x[m] = cf{v.x, v.y}; }
;     const cf w{wv.x, wv.y};
;     if (INV) dit_reg<LR>(x, w); else dif_reg<LR>(x, w);
; #pragma unroll
;     for (int m = 0; m < R; ++m) buf[base + m * stride] = mkv2(x[m].x, x[m].y);
; }
.LBB0_357:
	v_add_u32_e32 v69, s0, v68
	v_ashrrev_i32_e32 v72, 4, v69
	v_lshl_add_u32 v69, v69, 3, 0
	v_add_u32_e32 v73, 0x22000, v69
	ds_read_b64 v[88:89], v73
	v_lshl_add_u32 v69, v72, 3, v69
	ds_read2st64_b64 v[72:75], v69 offset1:17
	ds_read2st64_b64 v[76:79], v69 offset0:34 offset1:51
	ds_read2st64_b64 v[80:83], v69 offset0:68 offset1:85
	ds_read2st64_b64 v[84:87], v69 offset0:102 offset1:119
	s_movk_i32 s0, 0x200
	s_and_b64 vcc, exec, s[6:7]
	s_waitcnt lgkmcnt(4)
	v_pk_mul_f32 v[90:91], v[88:89], v[88:89]
	v_pk_mul_f32 v[92:93], v[88:89], v[88:89] op_sel:[0,1] op_sel_hi:[1,0]
	v_mov_b32_e32 v94, v90
	v_mov_b32_e32 v95, v92
	v_pk_mov_b32 v[90:91], v[90:91], v[92:93] op_sel:[1,0]
	s_waitcnt lgkmcnt(1)
	v_mov_b32_e32 v114, v80
	v_pk_add_f32 v[92:93], v[94:95], v[90:91] neg_lo:[0,1] neg_hi:[0,1]
	v_pk_add_f32 v[90:91], v[94:95], v[90:91]
	v_mov_b32_e32 v94, v92
	v_mov_b32_e32 v95, v91
	v_pk_mul_f32 v[98:99], v[94:95], v[94:95]
	v_pk_mul_f32 v[100:101], v[94:95], v[90:91] op_sel:[0,1] op_sel_hi:[1,0]
	v_mov_b32_e32 v112, v92
	v_mov_b32_e32 v101, v98
	v_mov_b32_e32 v98, v100
	v_pk_add_f32 v[102:103], v[100:101], v[98:99] neg_lo:[0,1] neg_hi:[0,1]
	v_pk_add_f32 v[98:99], v[100:101], v[98:99]
	v_mov_b32_e32 v101, v103
	v_mov_b32_e32 v100, v98
	s_waitcnt lgkmcnt(0)
	v_mul_f32_e32 v108, v103, v86
	v_mul_f32_e32 v110, v103, v87
	v_mul_f32_e32 v104, v103, v82
	v_mul_f32_e32 v106, v103, v83
	v_pk_fma_f32 v[108:109], v[100:101], v[86:87], v[108:109] op_sel:[0,1,0] op_sel_hi:[1,0,0]
	v_pk_fma_f32 v[86:87], v[100:101], v[86:87], v[110:111] op_sel_hi:[1,1,0] neg_lo:[1,0,0] neg_hi:[1,0,0]
	v_pk_fma_f32 v[104:105], v[100:101], v[82:83], v[104:105] op_sel:[0,1,0] op_sel_hi:[1,0,0]
	v_pk_fma_f32 v[82:83], v[100:101], v[82:83], v[106:107] op_sel_hi:[1,1,0] neg_lo:[1,0,0] neg_hi:[1,0,0]
	v_pk_add_f32 v[100:101], v[84:85], v[108:109]
	v_pk_add_f32 v[110:111], v[84:85], v[86:87] op_sel:[1,0] op_sel_hi:[0,1]
	v_mov_b32_e32 v113, v110
	v_mov_b32_e32 v101, v91
	v_pk_mul_f32 v[112:113], v[112:113], v[100:101]
	v_mov_b32_e32 v111, v91
	v_mov_b32_e32 v115, v112
	v_mov_b32_e32 v105, v113
	v_pk_add_f32 v[112:113], v[114:115], v[104:105]
	v_mov_b32_e32 v114, v92
	v_mov_b32_e32 v115, v100
	v_mul_f32_e32 v100, v100, v91
	v_pk_fma_f32 v[100:101], v[114:115], v[110:111], v[100:101] op_sel_hi:[1,1,0] neg_lo:[0,0,1] neg_hi:[0,0,1]
	v_pk_mul_f32 v[114:115], v[74:75], v[98:99] op_sel_hi:[1,0]
	v_pk_mul_f32 v[98:99], v[98:99], v[78:79] op_sel_hi:[0,1]
	v_pk_fma_f32 v[116:117], v[74:75], v[102:103], v[114:115] op_sel:[0,1,1] op_sel_hi:[1,1,0]
	v_pk_fma_f32 v[74:75], v[74:75], v[102:103], v[114:115] op_sel:[0,1,1] op_sel_hi:[1,1,0] neg_lo:[0,0,1] neg_hi:[0,0,1]
	v_pk_fma_f32 v[114:115], v[102:103], v[78:79], v[98:99] op_sel:[1,0,1] op_sel_hi:[1,1,0]
	v_pk_fma_f32 v[78:79], v[102:103], v[78:79], v[98:99] op_sel:[1,0,1] op_sel_hi:[1,1,0] neg_lo:[0,0,1] neg_hi:[0,0,1]
	v_pk_mov_b32 v[96:97], v[90:91], v[92:93] op_sel:[1,0]
	v_mov_b32_e32 v115, v79
	v_pk_add_f32 v[78:79], v[76:77], v[114:115]
	v_pk_add_f32 v[106:107], v[80:81], v[82:83] op_sel:[1,0] op_sel_hi:[0,1]
	v_pk_mul_f32 v[90:91], v[90:91], v[78:79] op_sel:[1,1] op_sel_hi:[1,0]
	v_pk_add_f32 v[110:111], v[106:107], v[100:101]
	v_pk_fma_f32 v[98:99], v[92:93], v[78:79], v[90:91]
	v_pk_fma_f32 v[78:79], v[92:93], v[78:79], v[90:91] op_sel_hi:[0,1,1] neg_lo:[0,0,1] neg_hi:[0,0,1]
	v_pk_add_f32 v[90:91], v[112:113], v[112:113] op_sel:[0,1] op_sel_hi:[0,1]
	v_mov_b32_e32 v117, v75
	v_pk_mul_f32 v[90:91], v[88:89], v[90:91]
	v_mov_b32_e32 v105, v82
	v_pk_add_f32 v[82:83], v[84:85], v[86:87] op_sel:[1,0] op_sel_hi:[1,0] neg_lo:[0,1] neg_hi:[0,1]
	v_pk_add_f32 v[108:109], v[84:85], v[108:109] neg_lo:[0,1] neg_hi:[0,1]
	v_pk_add_f32 v[74:75], v[72:73], v[116:117]
	v_mov_b32_e32 v99, v79
	v_pk_fma_f32 v[92:93], v[88:89], v[110:111], v[90:91] op_sel:[1,0,0] op_sel_hi:[0,1,1]
	v_pk_fma_f32 v[90:91], v[88:89], v[110:111], v[90:91] op_sel:[1,0,0] op_sel_hi:[0,0,1] neg_lo:[0,0,1] neg_hi:[0,0,1]
	v_pk_mul_f32 v[82:83], v[94:95], v[82:83]
	v_pk_add_f32 v[76:77], v[76:77], v[114:115] neg_lo:[0,1] neg_hi:[0,1]
	v_pk_add_f32 v[78:79], v[74:75], v[98:99]
	v_mov_b32_e32 v93, v91
	v_pk_fma_f32 v[84:85], v[96:97], v[108:109], v[82:83] neg_lo:[0,0,1] neg_hi:[0,0,1]
	v_pk_fma_f32 v[82:83], v[96:97], v[108:109], v[82:83] op_sel_hi:[1,0,1]
	v_pk_add_f32 v[90:91], v[78:79], v[92:93]
	v_pk_add_f32 v[78:79], v[78:79], v[92:93] neg_lo:[0,1] neg_hi:[0,1]
	v_pk_mul_f32 v[92:93], v[88:89], s[16:17] op_sel_hi:[1,0]
	v_pk_add_f32 v[80:81], v[80:81], v[104:105] neg_lo:[0,1] neg_hi:[0,1]
	v_mov_b32_e32 v85, v83
	v_pk_mul_f32 v[86:87], v[94:95], v[76:77] op_sel:[0,1]
	v_pk_add_f32 v[82:83], v[80:81], v[84:85]
	v_pk_fma_f32 v[94:95], v[96:97], v[76:77], v[86:87] neg_lo:[0,0,1] neg_hi:[0,0,1]
	v_pk_fma_f32 v[76:77], v[96:97], v[76:77], v[86:87] op_sel_hi:[1,0,1]
	v_pk_add_f32 v[96:97], v[92:93], v[92:93] op_sel:[1,0] op_sel_hi:[1,0] neg_lo:[0,1] neg_hi:[0,1]
	v_pk_add_f32 v[86:87], v[92:93], v[92:93] op_sel:[0,1] op_sel_hi:[0,1]
	v_pk_mul_f32 v[102:103], v[96:97], v[82:83]
	v_pk_add_f32 v[74:75], v[74:75], v[98:99] neg_lo:[0,1] neg_hi:[0,1]
	v_pk_fma_f32 v[104:105], v[86:87], v[82:83], v[102:103] op_sel:[0,0,1] op_sel_hi:[1,1,0]
	v_pk_fma_f32 v[82:83], v[86:87], v[82:83], v[102:103] op_sel:[0,0,1] op_sel_hi:[1,1,0] neg_lo:[0,0,1] neg_hi:[0,0,1]
	v_sub_f32_e32 v86, v106, v100
	v_pk_mul_f32 v[86:87], v[88:89], v[86:87] op_sel_hi:[1,0]
	v_pk_add_f32 v[98:99], v[112:113], v[112:113] op_sel:[0,1] op_sel_hi:[0,1] neg_lo:[0,1] neg_hi:[0,1]
	v_pk_fma_f32 v[100:101], v[88:89], v[98:99], v[86:87] op_sel:[1,0,0] op_sel_hi:[0,1,1] neg_lo:[0,0,1] neg_hi:[0,0,1]
	v_pk_fma_f32 v[86:87], v[88:89], v[98:99], v[86:87] op_sel:[1,0,0] op_sel_hi:[0,1,1]
	v_fma_f32 v88, v89, s87, -v92
	v_pk_add_f32 v[80:81], v[80:81], v[84:85] neg_lo:[0,1] neg_hi:[0,1]
	v_pk_add_f32 v[72:73], v[72:73], v[116:117] neg_lo:[0,1] neg_hi:[0,1]
	v_mov_b32_e32 v95, v77
	v_pk_mul_f32 v[84:85], v[88:89], v[80:81] op_sel:[0,1] op_sel_hi:[0,0]
	v_pk_add_f32 v[76:77], v[72:73], v[94:95]
	v_mov_b32_e32 v105, v83
	v_pk_fma_f32 v[88:89], v[96:97], v[80:81], v[84:85]
	v_pk_fma_f32 v[80:81], v[96:97], v[80:81], v[84:85] neg_lo:[0,0,1] neg_hi:[0,0,1]
	v_pk_add_f32 v[82:83], v[76:77], v[104:105]
	v_mov_b32_e32 v101, v87
	v_pk_add_f32 v[72:73], v[72:73], v[94:95] neg_lo:[0,1] neg_hi:[0,1]
	v_mov_b32_e32 v89, v81
	s_mov_b64 s[6:7], 0
	v_pk_add_f32 v[76:77], v[76:77], v[104:105] neg_lo:[0,1] neg_hi:[0,1]
	v_pk_add_f32 v[86:87], v[74:75], v[100:101]
	v_pk_add_f32 v[74:75], v[74:75], v[100:101] neg_lo:[0,1] neg_hi:[0,1]
	v_pk_add_f32 v[80:81], v[72:73], v[88:89]
	v_pk_add_f32 v[72:73], v[72:73], v[88:89] neg_lo:[0,1] neg_hi:[0,1]
	ds_write2st64_b64 v69, v[90:91], v[82:83] offset1:17
	ds_write2st64_b64 v69, v[86:87], v[80:81] offset0:34 offset1:51
	ds_write2st64_b64 v69, v[78:79], v[76:77] offset0:68 offset1:85
	ds_write2st64_b64 v69, v[74:75], v[72:73] offset0:102 offset1:119
	s_cbranch_vccnz .LBB0_357
; __device__ __forceinline__ float bf2f(bf16_t b) { return __uint_as_float(((unsigned)b) << 16); }
; __device__ __forceinline__ void sconv8(const Raw8& r, int n0, float w0, float w1, float w2, float b, float (&out)[8]) {
;     float a[10]; a[0] = n0 > 0 ? bf2f(r.eL) : 0.f; a[9] = n0 + 8 < SEQ ? bf2f(r.eR) : 0.f;
;     a[1] = __uint_as_float(r.body.x << 16); a[2] = __uint_as_float(r.body.x & 0xffff0000u); a[3] = __uint_as_float(r.body.y << 16); a[4] = __uint_as_float(r.body.y & 0xffff0000u);
;     a[5] = __uint_as_float(r.body.z << 16); a[6] = __uint_as_float(r.body.z & 0xffff0000u); a[7] = __uint_as_float(r.body.w << 16); a[8] = __uint_as_float(r.body.w & 0xffff0000u);
; #pragma unroll
;     for (int k = 0; k < 8; ++k) out[k] = w0 * a[k] + w1 * a[k + 1] + w2 * a[k + 2] + b;
; }
; __device__ void ph_hyena_fft(const Params& P, int j, const bf16_t* __restrict__ projAT, const float* __restrict__ kf, bf16_t* __restrict__ yaT, unsigned char* lds_raw) {
;     ...
;             { float xa[8], xb[8]; sconv8(xa0, n0, wa0, wa1, wa2, ba, xa); sconv8(xa1, n0, wa0, wa1, wa2, ba, xb);
; #pragma unroll
;               for (int k = 0; k < 8; ++k) { const v2f y = buf[ph0 + k]; va[k] = xa[k] * (y.x * invN + sk0 * va[k]); vb[k] = xb[k] * (y.y * invN + sk0 * vb[k]);
	s_waitcnt vmcnt(5)
	v_lshlrev_b32_e32 v68, 16, v143
	v_cndmask_b32_e64 v69, 0, v68, s[42:43]
	s_waitcnt vmcnt(3)
	v_lshlrev_b32_e32 v68, 16, v144
	v_lshlrev_b32_e32 v75, 16, v5
	v_cndmask_b32_e64 v73, 0, v68, s[44:45]
	v_lshlrev_b32_e32 v74, 16, v4
	v_and_b32_e32 v76, 0xffff0000, v4
	v_mov_b32_e32 v68, v75
	v_and_b32_e32 v77, 0xffff0000, v5
	v_mov_b32_e32 v80, v74
	v_mov_b32_e32 v81, v76
	v_pk_mul_f32 v[68:69], v[56:57], v[68:69]
	v_lshlrev_b32_e32 v79, 16, v6
	v_pk_fma_f32 v[68:69], v[56:57], v[80:81], v[68:69] op_sel:[0,0,1] op_sel_hi:[1,1,0]
	v_pk_mul_f32 v[80:81], v[32:33], v[76:77]
	v_and_b32_e32 v5, 0xffff0000, v7
	v_mov_b32_e32 v78, v75
	v_pk_fma_f32 v[74:75], v[30:31], v[74:75], v[80:81]
	v_and_b32_e32 v81, 16, v7
	v_and_b32_e32 v80, 0xffff0000, v6
	v_lshlrev_b32_e32 v7, 16, v7
	v_pk_fma_f32 v[68:69], v[34:35], v[76:77], v[68:69]
	v_mov_b32_e32 v6, v80
	v_mov_b32_e32 v4, v80
	v_pk_mov_b32 v[76:77], v[76:77], v[80:81] op_sel:[1,0]
	v_mov_b32_e32 v80, v79
	v_mov_b32_e32 v81, v7
	v_pk_mul_f32 v[80:81], v[32:33], v[80:81]
	v_pk_fma_f32 v[74:75], v[34:35], v[78:79], v[74:75]
	v_pk_fma_f32 v[76:77], v[30:31], v[76:77], v[80:81]
	v_mov_b32_e32 v78, v5
	v_pk_fma_f32 v[80:81], v[34:35], v[4:5], v[76:77]
	v_pk_mul_f32 v[4:5], v[56:57], v[78:79]
	v_mov_b32_e32 v72, v7
	v_pk_fma_f32 v[4:5], v[56:57], v[6:7], v[4:5] op_sel:[0,0,1] op_sel_hi:[1,1,0]
	s_waitcnt vmcnt(1)
	v_lshlrev_b32_e32 v77, 16, v1
	v_pk_fma_f32 v[72:73], v[34:35], v[72:73], v[4:5]
	v_lshlrev_b32_e32 v4, 16, v139
	v_cndmask_b32_e64 v5, 0, v4, s[42:43]
	s_waitcnt vmcnt(0)
	v_lshlrev_b32_e32 v4, 16, v141
	v_cndmask_b32_e64 v7, 0, v4, s[44:45]
	v_lshlrev_b32_e32 v76, 16, v0
	v_and_b32_e32 v78, 0xffff0000, v0
	v_mov_b32_e32 v4, v77
	v_mov_b32_e32 v84, v76
	v_mov_b32_e32 v85, v78
	v_pk_mul_f32 v[4:5], v[56:57], v[4:5]
	v_and_b32_e32 v79, 0xffff0000, v1
	v_pk_fma_f32 v[4:5], v[56:57], v[84:85], v[4:5] op_sel:[0,0,1] op_sel_hi:[1,1,0]
	v_lshlrev_b32_e32 v83, 16, v2
	v_pk_fma_f32 v[84:85], v[34:35], v[78:79], v[4:5]
	v_pk_mul_f32 v[4:5], v[32:33], v[78:79]
	v_mov_b32_e32 v82, v77
	v_pk_fma_f32 v[4:5], v[30:31], v[76:77], v[4:5]
	v_and_b32_e32 v1, 0xffff0000, v3
	v_pk_fma_f32 v[86:87], v[34:35], v[82:83], v[4:5]
	v_and_b32_e32 v5, 16, v3
	v_lshlrev_b32_e32 v3, 16, v3
	v_and_b32_e32 v4, 0xffff0000, v2
	v_mov_b32_e32 v76, v83
	v_mov_b32_e32 v77, v3
	v_mov_b32_e32 v2, v4
	v_mov_b32_e32 v0, v4
	v_pk_mov_b32 v[4:5], v[78:79], v[4:5] op_sel:[1,0]
	v_pk_mul_f32 v[76:77], v[32:33], v[76:77]
	v_mov_b32_e32 v82, v1
	v_pk_fma_f32 v[4:5], v[30:31], v[4:5], v[76:77]
	s_waitcnt lgkmcnt(0)
	s_barrier
; __device__ __forceinline__ uint4 ntld_u4(const void* p) { const ntu4_t v = __builtin_nontemporal_load((const ntu4_t*)p); return make_uint4(v.x, v.y, v.z, v.w); }
; __device__ __forceinline__ void lds_barrier() { asm volatile("s_waitcnt lgkmcnt(0)\n\ts_barrier" ::: "memory"); }
; __device__ void ph_hyena_fft(const Params& P, int j, const bf16_t* __restrict__ projAT, const float* __restrict__ kf, bf16_t* __restrict__ yaT, unsigned char* lds_raw) {
;     ...
;             { float xa[8], xb[8]; sconv8(xa0, n0, wa0, wa1, wa2, ba, xa); sconv8(xa1, n0, wa0, wa1, wa2, ba, xb);
; #pragma unroll
;               for (int k = 0; k < 8; ++k) { const v2f y = buf[ph0 + k]; va[k] = xa[k] * (y.x * invN + sk0 * va[k]); vb[k] = xb[k] * (y.y * invN + sk0 * vb[k]);
;                   buf[ph0 + k] = mkv2(va[k], vb[k]); buf[ph0 + 4352 + k] = mkv2(0.f, 0.f); } }
;             const Raw8 xb0 = load_raw8(x2row + o0, n0), xb1 = load_raw8(x2row + o1, n0);
;             const uint4 g0 = ntld_u4(grow + o0 + n0), g1 = ntld_u4(grow + o1 + n0);
;             lds_barrier();
	v_mov_b32_e32 v6, v3
	v_pk_fma_f32 v[78:79], v[34:35], v[0:1], v[4:5]
	v_pk_mul_f32 v[0:1], v[56:57], v[82:83]
	v_pk_add_f32 v[74:75], v[36:37], v[74:75]
	v_pk_fma_f32 v[0:1], v[56:57], v[2:3], v[0:1] op_sel:[0,0,1] op_sel_hi:[1,1,0]
	v_pk_add_f32 v[68:69], v[36:37], v[68:69]
	v_pk_fma_f32 v[82:83], v[34:35], v[6:7], v[0:1]
	ds_read2_b64 v[0:3], v145 offset1:1
	ds_read2_b64 v[4:7], v145 offset0:2 offset1:3
	s_mov_b32 s14, 0
	s_mov_b32 s15, s14
	s_mov_b32 s0, s14
	s_waitcnt lgkmcnt(1)
	v_mov_b32_e32 v76, v0
	s_waitcnt lgkmcnt(0)
	v_mov_b32_e32 v77, v4
	v_mov_b32_e32 v4, v1
	v_pk_mul_f32 v[0:1], v[4:5], s[80:81] op_sel_hi:[1,0]
	v_mov_b32_e32 v4, v2
	v_mov_b32_e32 v5, v6
	v_pk_mul_f32 v[4:5], v[4:5], s[80:81] op_sel_hi:[1,0]
	v_pk_mul_f32 v[76:77], v[76:77], s[80:81] op_sel_hi:[1,0]
	v_pk_fma_f32 v[4:5], v[44:45], v[62:63], v[4:5]
	v_mov_b32_e32 v6, v3
	v_pk_fma_f32 v[64:65], v[44:45], v[64:65], v[76:77]
	v_pk_mul_f32 v[74:75], v[74:75], v[4:5]
	v_pk_mul_f32 v[2:3], v[6:7], s[80:81] op_sel_hi:[1,0]
	v_pk_add_f32 v[4:5], v[36:37], v[84:85]
	v_pk_fma_f32 v[0:1], v[44:45], v[66:67], v[0:1]
	v_pk_mul_f32 v[76:77], v[68:69], v[64:65]
	v_pk_add_f32 v[6:7], v[36:37], v[86:87]
	v_pk_mul_f32 v[68:69], v[4:5], v[0:1]
	v_pk_fma_f32 v[0:1], v[44:45], v[70:71], v[2:3]
	s_mov_b32 s1, s14
	v_pk_mul_f32 v[66:67], v[6:7], v[0:1]
	v_mov_b32_e32 v0, v76
	v_mov_b32_e32 v1, v68
	v_mov_b32_e32 v2, v74
	v_mov_b32_e32 v3, v66
	v_mov_b64_e32 v[88:89], s[14:15]
	v_mov_b64_e32 v[90:91], s[0:1]
	ds_write2_b64 v145, v[0:1], v[2:3] offset1:1
	v_mov_b32_e32 v0, v77
	v_mov_b32_e32 v1, v69
	v_mov_b32_e32 v2, v75
	v_mov_b32_e32 v3, v67
	ds_write2_b64 v142, v[88:89], v[90:91] offset1:1
	ds_write2_b64 v145, v[0:1], v[2:3] offset0:2 offset1:3
	ds_write2_b64 v138, v[88:89], v[90:91] offset1:1
	ds_read2_b64 v[0:3], v145 offset0:4 offset1:5
	ds_read2_b64 v[4:7], v145 offset0:6 offset1:7
	v_pk_add_f32 v[70:71], v[36:37], v[72:73]
	v_pk_add_f32 v[64:65], v[36:37], v[80:81]
	s_lshl_b32 s62, s11, 1
	s_waitcnt lgkmcnt(1)
	v_mov_b32_e32 v62, v0
	s_waitcnt lgkmcnt(0)
	v_mov_b32_e32 v63, v4
	v_mov_b32_e32 v4, v1
	v_pk_mul_f32 v[0:1], v[4:5], s[80:81] op_sel_hi:[1,0]
	v_mov_b32_e32 v4, v2
	v_mov_b32_e32 v5, v6
	v_pk_mul_f32 v[4:5], v[4:5], s[80:81] op_sel_hi:[1,0]
	v_pk_mul_f32 v[62:63], v[62:63], s[80:81] op_sel_hi:[1,0]
	v_pk_fma_f32 v[4:5], v[44:45], v[10:11], v[4:5]
	v_mov_b32_e32 v6, v3
	v_pk_fma_f32 v[8:9], v[44:45], v[8:9], v[62:63]
	v_pk_mul_f32 v[70:71], v[70:71], v[4:5]
	v_pk_mul_f32 v[2:3], v[6:7], s[80:81] op_sel_hi:[1,0]
	v_pk_add_f32 v[4:5], v[36:37], v[78:79]
	v_pk_fma_f32 v[0:1], v[44:45], v[12:13], v[0:1]
	v_pk_mul_f32 v[72:73], v[64:65], v[8:9]
	v_pk_add_f32 v[6:7], v[36:37], v[82:83]
	v_pk_mul_f32 v[64:65], v[4:5], v[0:1]
	v_pk_fma_f32 v[0:1], v[44:45], v[14:15], v[2:3]
	v_mov_b32_e32 v2, v70
	v_pk_mul_f32 v[62:63], v[6:7], v[0:1]
	v_mov_b32_e32 v0, v72
	v_mov_b32_e32 v1, v64
	v_mov_b32_e32 v3, v62
	s_add_u32 s0, s61, s62
	ds_write2_b64 v145, v[0:1], v[2:3] offset0:4 offset1:5
	v_mov_b32_e32 v0, v73
	v_mov_b32_e32 v1, v65
	v_mov_b32_e32 v2, v71
	v_mov_b32_e32 v3, v63
	s_addc_u32 s1, s52, 0
	ds_write2_b64 v140, v[88:89], v[90:91] offset1:1
	ds_write2_b64 v145, v[0:1], v[2:3] offset0:6 offset1:7
	ds_write2_b64 v137, v[88:89], v[90:91] offset1:1
	v_lshl_add_u64 v[0:1], s[0:1], 0, v[16:17]
	s_lshl_b32 s6, s10, 1
	global_load_dwordx4 v[4:7], v[0:1], off nt
	global_load_ushort v147, v146, s[0:1] offset:-2
	v_lshl_add_u64 v[0:1], s[0:1], 0, v[22:23]
	s_add_u32 s0, s61, s6
	s_addc_u32 s1, s52, 0
	global_load_ushort v148, v[0:1], off offset:16
	v_lshl_add_u64 v[0:1], s[0:1], 0, v[16:17]
	global_load_dwordx4 v[8:11], v[0:1], off nt
	global_load_ushort v149, v146, s[0:1] offset:-2
	v_lshl_add_u64 v[0:1], s[0:1], 0, v[22:23]
	s_mov_b32 s7, s63
	global_load_ushort v150, v[0:1], off offset:16
	v_lshl_add_u64 v[0:1], v[48:49], 0, s[62:63]
	global_load_dwordx4 v[12:15], v[0:1], off nt
	v_lshl_add_u64 v[0:1], v[48:49], 0, s[6:7]
	global_load_dwordx4 v[0:3], v[0:1], off nt
	s_cmp_eq_u32 s53, 3
	s_cbranch_scc1 .Lhy_nopf
	s_add_i32 s100, s53, 1
	s_lshl_b32 s100, s100, 14
	s_add_u32 s100, s47, s100
	s_addc_u32 s101, s58, 0
	v_lshl_add_u64 v[188:189], s[100:101], 0, v[16:17]
	v_lshl_add_u64 v[190:191], s[100:101], 0, v[22:23]
	global_load_ushort v184, v146, s[100:101] offset:-2
	global_load_dwordx4 v[176:179], v[188:189], off nt
	s_add_u32 s100, s100, 0x2000
	s_addc_u32 s101, s101, 0
	v_lshl_add_u64 v[188:189], s[100:101], 0, v[22:23]
	global_load_ushort v185, v146, s[100:101] offset:-2
	global_load_ushort v186, v[188:189], off offset:16
	global_load_ushort v187, v[190:191], off offset:16
	v_lshl_add_u64 v[188:189], s[100:101], 0, v[16:17]
	global_load_dwordx4 v[180:183], v[188:189], off nt
.Lhy_nopf:
	s_waitcnt lgkmcnt(0)
	s_barrier
	v_mov_b32_e32 v78, v195
	s_mov_b64 s[10:11], -1

; #define LAS __attribute__((address_space(3)))
; __device__ __forceinline__ int otid() { int t = threadIdx.x; asm volatile("" : "+v"(t)); return t; }
;     __device__ __forceinline__ void init(int n, int hh) { rq = r0 + (n >> 4); const int cq = c0 + (n & 15); rsq = rq - 4; rsq = rsq < 0 ? 0 : (rsq > 56 ? 56 : rsq); int csq = cq - 8; csq = csq < 0 ? 0 : (csq > 48 ? 48 : csq);
;         cbase = cw0 + 4 * hh - cq + 15; int m = 0;
; #pragma unroll
;         for (int i = 0; i < 16; ++i) { const int ck = cw0 + 4 * hh + CI32(i); m |= (ck >= csq && ck < csq + 16) ? (1 << i) : 0; }
;         colmask = m; }
; __device__ void ph_natten_mfma(const Params& P, int j, int half, const bf16_t* __restrict__ proj, bf16_t* __restrict__ yout, unsigned char* lds_raw) {
;     const int tid = otid(); const int lane = tid & 63, wid = tid >> 6;
;     LAS float* tbl = (LAS float*)lds_raw; LAS unsigned char* wl = (LAS unsigned char*)lds_raw + 32768 + wid * 4608;
;     const float* rpb = P.in[18] + (size_t)j * 32 * 15 * 31;
;     const int G = gridDim.x, bid = blockIdx.x, vb = (G % 8 == 0) ? (bid & 7) * (G >> 3) + (bid >> 3) : bid;
; #pragma unroll 1
;     for (int id0 = vb * 8; id0 < 8192; id0 += G * 8) {
;         const int p = id0 >> 6, b = p >> 4, h = p & 15, wt = (id0 & 63) + wid;
;         __syncthreads();
;         for (int x = tid; x < 465; x += NT) tbl[64 + x] = rpb[(size_t)(half * 16 + h) * 465 + x] * 1.44269504088896341f;
;         __syncthreads();
;         const int r0 = (wt >> 2) * 4, c0 = (wt & 3) * 16;
;         int rs0 = r0 - 4; rs0 = rs0 < 0 ? 0 : (rs0 > 56 ? 56 : rs0); int cw0 = c0 - 8; cw0 = cw0 < 0 ? 0 : (cw0 > 32 ? 32 : cw0);
;         NatPol polA{r0, c0, rs0, cw0, tbl + 64, 0, 0, 0, 0}, polB{r0 + 2, c0, rs0, cw0, tbl + 64, 0, 0, 0, 0};
.LBB0_372:
	v_readlane_b32 s0, v255, 47
	v_readlane_b32 s1, v255, 48
	s_andn2_b64 vcc, exec, s[0:1]
	s_cbranch_vccnz .LBB0_390
	v_readlane_b32 s0, v254, 25
	v_readlane_b32 s1, v254, 26
	v_mov_b32_e32 v160, v195
	s_andn2_b64 vcc, exec, s[0:1]
	s_cbranch_vccnz .LBB0_390
	v_readlane_b32 s0, v255, 50
	v_ashrrev_i32_e32 v176, 6, v160
	s_mul_i32 s0, s0, 0xe880
	s_add_u32 s12, s68, s0
	s_movk_i32 s0, 0x1200
	v_lshlrev_b32_e32 v2, 4, v176
	v_mul_lo_u32 v0, v176, s0
	v_and_b32_e32 v2, 48, v2
	v_add_u32_e32 v1, 0, v0
	v_and_b32_e32 v0, 63, v160
	v_med3_u32 v3, v2, 8, 40
	v_bfe_u32 v7, v160, 5, 1
	v_and_or_b32 v178, v160, 15, v2
	v_add_u32_e32 v5, -8, v3
	v_lshlrev_b32_e32 v4, 2, v0
	v_med3_u32 v2, v178, 8, 56
	v_lshlrev_b32_e32 v0, 2, v7
	v_add_u32_e32 v8, -8, v2
	v_or_b32_e32 v9, v5, v0
	v_add_u32_e32 v10, 8, v2
	v_readlane_b32 s1, v255, 51
	s_movk_i32 s0, 0x1d1
	v_cmp_ge_u32_e32 vcc, v9, v8
	v_cmp_lt_u32_e64 s[44:45], v9, v10
	v_or_b32_e32 v11, 1, v9
	s_addc_u32 s17, s69, 0
	v_cmp_gt_i32_e64 s[42:43], s0, v160
	s_and_b64 s[0:1], vcc, s[44:45]
	v_cmp_ge_u32_e32 vcc, v11, v8
	v_cmp_lt_u32_e64 s[44:45], v11, v10
	v_or_b32_e32 v12, 2, v9
	s_and_b64 s[6:7], vcc, s[44:45]
	v_cmp_ge_u32_e32 vcc, v12, v8
	v_cmp_lt_u32_e64 s[44:45], v12, v10
	v_or_b32_e32 v13, 3, v9
	v_cndmask_b32_e64 v11, 0, 2, s[6:7]
	s_and_b64 s[6:7], vcc, s[44:45]
	v_cmp_ge_u32_e32 vcc, v13, v8
	v_cmp_lt_u32_e64 s[44:45], v13, v10
	v_add_u32_e32 v14, 8, v9
	v_cndmask_b32_e64 v12, 0, 4, s[6:7]
	s_and_b64 s[6:7], vcc, s[44:45]
	v_cmp_ge_u32_e32 vcc, v14, v8
	v_cmp_lt_u32_e64 s[44:45], v9, v2
	v_add_u32_e32 v2, 9, v9
	v_cndmask_b32_e64 v13, 0, 8, s[6:7]
	s_and_b64 s[6:7], s[44:45], vcc
	v_cmp_ge_u32_e32 vcc, v2, v8
	v_cmp_lt_u32_e64 s[44:45], v2, v10
	v_add_u32_e32 v2, 10, v9
	v_cndmask_b32_e64 v14, 0, 16, s[6:7]
	s_and_b64 s[6:7], vcc, s[44:45]
	v_cmp_ge_u32_e32 vcc, v2, v8
	v_cmp_lt_u32_e64 s[44:45], v2, v10
	v_add_u32_e32 v2, 11, v9
	v_cndmask_b32_e64 v15, 0, 32, s[6:7]
	s_and_b64 s[6:7], vcc, s[44:45]
	v_cmp_ge_u32_e32 vcc, v2, v8
	v_cmp_lt_u32_e64 s[44:45], v2, v10
	s_and_b64 vcc, vcc, s[44:45]
	v_mov_b32_e32 v2, 0x80
	v_cndmask_b32_e32 v17, 0, v2, vcc
	v_add_u32_e32 v2, 16, v9
	v_cmp_ge_u32_e32 vcc, v2, v8
	v_cmp_lt_u32_e64 s[44:45], v2, v10
	s_and_b64 vcc, vcc, s[44:45]
	v_mov_b32_e32 v2, 0x100
	v_cndmask_b32_e32 v18, 0, v2, vcc
	v_add_u32_e32 v2, 17, v9
	v_cmp_ge_u32_e32 vcc, v2, v8
	v_cmp_lt_u32_e64 s[44:45], v2, v10
	s_and_b64 vcc, vcc, s[44:45]
	v_mov_b32_e32 v2, 0x200
	v_cndmask_b32_e32 v19, 0, v2, vcc
	v_add_u32_e32 v2, 18, v9
	v_cmp_ge_u32_e32 vcc, v2, v8
	v_cmp_lt_u32_e64 s[44:45], v2, v10
	s_and_b64 vcc, vcc, s[44:45]
	v_mov_b32_e32 v2, 0x400
	v_cndmask_b32_e32 v20, 0, v2, vcc
	v_add_u32_e32 v2, 19, v9
	v_cmp_ge_u32_e32 vcc, v2, v8
	v_cmp_lt_u32_e64 s[44:45], v2, v10
	s_and_b64 vcc, vcc, s[44:45]
	v_mov_b32_e32 v2, 0x800
	v_cndmask_b32_e32 v21, 0, v2, vcc
	v_add_u32_e32 v2, 24, v9
	v_cmp_ge_u32_e32 vcc, v2, v8
	v_cmp_lt_u32_e64 s[44:45], v2, v10
	s_and_b64 vcc, vcc, s[44:45]
	v_add_u32_e32 v2, 25, v9
	v_cndmask_b32_e32 v22, 0, v231, vcc
	v_cmp_ge_u32_e32 vcc, v2, v8
	v_cmp_lt_u32_e64 s[44:45], v2, v10
	s_and_b64 vcc, vcc, s[44:45]
	v_add_u32_e32 v2, 26, v9
	v_cndmask_b32_e32 v23, 0, v238, vcc
	v_cmp_ge_u32_e32 vcc, v2, v8
	v_cmp_lt_u32_e64 s[44:45], v2, v10
	v_add_u32_e32 v2, 27, v9
	v_cndmask_b32_e64 v9, 0, 1, s[0:1]
	v_or_b32_e32 v9, v11, v9
	v_or3_b32 v9, v9, v12, v13
	v_cndmask_b32_e64 v16, 0, 64, s[6:7]
	v_or3_b32 v9, v9, v14, v15
	s_and_b64 vcc, vcc, s[44:45]
	v_or3_b32 v9, v9, v16, v17
	v_cndmask_b32_e32 v24, 0, v230, vcc
	v_cmp_ge_u32_e32 vcc, v2, v8
	v_cmp_lt_u32_e64 s[44:45], v2, v10
	v_or3_b32 v9, v9, v18, v19
	s_and_b64 vcc, vcc, s[44:45]
	v_mov_b32_e32 v2, 0x8000
	v_or3_b32 v9, v9, v20, v21
	v_cndmask_b32_e32 v8, 0, v2, vcc
	v_or3_b32 v9, v9, v22, v23
	v_and_b32_e32 v6, 31, v160
	v_or3_b32 v179, v9, v24, v8
	v_bfe_u32 v8, v160, 3, 3
	v_add_lshl_u32 v181, v5, v6, 6
	v_or_b32_e32 v5, v5, v8
	v_lshlrev_b32_e32 v182, 6, v5
	v_or_b32_e32 v5, v3, v8
	v_lshlrev_b32_e32 v183, 6, v5
	v_lshlrev_b32_e32 v5, 4, v160
	v_and_b32_e32 v5, 0x70, v5
	s_movk_i32 s0, 0x240
	v_lshlrev_b32_e32 v2, 3, v7
	v_add_u32_e32 v5, v1, v5
	v_mad_u32_u24 v1, v7, s0, v1
	v_mul_u32_u24_e32 v7, 0x90, v8
	v_max_i32_e32 v8, 0xffffffd1, v160
	v_sub_u32_e32 v8, v8, v160
	v_add_u32_e32 v8, 0x1ff, v8
	v_lshrrev_b32_e32 v9, 9, v8
	v_xor_b32_e32 v180, 0x80, v4
	v_lshlrev_b32_e32 v4, 3, v160
	v_add_u32_e32 v9, 1, v9
	v_or_b32_e32 v3, v3, v0
	s_add_i32 s35, 0, 0x100
	v_readlane_b32 s0, v255, 56
	v_and_b32_e32 v4, 56, v4
	v_lshlrev_b32_e32 v6, 1, v6
	v_and_b32_e32 v186, 0xfffffe, v9
	v_sub_u32_e32 v3, v3, v178
	s_add_u32 s38, s68, s0
	v_bfe_u32 v177, v160, 4, 1
	v_add_u32_e32 v184, 0x200, v183
	v_add_u32_e32 v185, 0x400, v183
	v_cmp_lt_u32_e64 s[44:45], s82, v8
	v_lshl_add_u32 v187, v186, 9, v160
	v_add_u32_e32 v161, 0x200, v160
	v_cmp_ne_u32_e64 s[46:47], v9, v186
	v_lshl_add_u32 v188, v3, 2, 0
	v_lshlrev_b32_e32 v189, 2, v160
	s_addc_u32 s39, s69, s93
	v_lshlrev_b32_e32 v192, 1, v2
	v_lshlrev_b32_e32 v162, 1, v4
	v_add_u32_e32 v190, v5, v7
	v_add_u32_e32 v191, v1, v6
	v_lshlrev_b32_e32 v164, 1, v0
	v_readlane_b32 s52, v254, 29
	v_lshrrev_b32_e32 v191, 6, v195
	v_mul_u32_u24_e32 v191, 0x1200, v191
	v_bfe_u32 v198, v195, 5, 1
	v_mul_u32_u24_e32 v198, 0x240, v198
	v_add_u32_e32 v191, v191, v198
	v_bfe_u32 v198, v195, 2, 2
	v_mul_u32_u24_e32 v198, 0x90, v198
	v_add_u32_e32 v191, v191, v198
	v_bfe_u32 v198, v195, 4, 1
	v_lshl_add_u32 v191, v198, 5, v191
	v_and_b32_e32 v198, 3, v195
	v_lshl_add_u32 v191, v198, 3, v191
	s_mov_b32 s101, -1
	s_branch .LBB0_376

; __device__ void ph_natten_mfma(const Params& P, int j, int half, const bf16_t* __restrict__ proj, bf16_t* __restrict__ yout, unsigned char* lds_raw) {
;     ...
;     for (int id0 = vb * 8; id0 < 8192; id0 += G * 8) {
;         const int p = id0 >> 6, b = p >> 4, h = p & 15, wt = (id0 & 63) + wid;
;         __syncthreads();
;         for (int x = tid; x < 465; x += NT) tbl[64 + x] = rpb[(size_t)(half * 16 + h) * 465 + x] * 1.44269504088896341f;
;         __syncthreads();
.LBB0_376:
	s_bfe_u32 s0, s52, 0x40006
	s_mov_b32 s100, 1
	s_mov_b64 s[6:7], exec
	s_cmp_eq_u32 s0, s101
	s_cbranch_scc1 .LBB0_386
	s_mov_b32 s100, 0
	s_mov_b32 s101, s0
	s_waitcnt vmcnt(0)
	s_barrier
	s_and_saveexec_b64 s[6:7], s[42:43]
	s_cbranch_execz .LBB0_386
	s_mov_b64 s[14:15], -1
	v_mov_b32_e32 v0, v160
	v_mov_b32_e32 v1, v189
	s_and_saveexec_b64 s[10:11], s[44:45]
	s_cbranch_execz .LBB0_383
	s_mul_i32 s1, s0, 0x744
	s_add_u32 s14, s12, s1
	s_addc_u32 s15, s17, 0
	s_mov_b64 s[30:31], 0
	v_mov_b32_e32 v2, v186
	v_add_u32_e32 v3, s35, v189
	v_mov_b64_e32 v[0:1], v[160:161]

; #define LAS __attribute__((address_space(3)))
;     __device__ __forceinline__ int qtok(int n) const { return (r0 + (n >> 4)) * 64 + c0 + (n & 15); }
; __device__ __forceinline__ void natten_wave_task2(const bf16_t* __restrict__ proj, int b, int h, NatPol pA, NatPol pB, bf16_t* __restrict__ yout, int lane, LAS unsigned char* wl) {
;     const int r = lane & 31, hh = lane >> 5, xaddr = (lane ^ 32) << 2;
;     pA.init(r, hh); pB.init(r, hh);
;     const int qtA = pA.qtok(r), qtB = pB.qtok(r);
;     const bf16_t* qbase = proj + (size_t)(b * 16 + h) * (4096 * 64); const bf16_t* kbase = qbase + (size_t)T_TOK * 1024; const bf16_t* vbase = kbase + (size_t)T_TOK * 1024; const bf16_t* gbase = vbase + (size_t)T_TOK * 1024;
;     bf16x8s qA[4], qB[4];
; #pragma unroll
;     for (int s = 0; s < 4; ++s) { qA[s] = *(const bf16x8s*)(qbase + qtA * 64 + 16 * s + 8 * hh); qB[s] = *(const bf16x8s*)(qbase + qtB * 64 + 16 * s + 8 * hh); }
;     f32x16 oA0, oA1, oB0, oB1;
; #pragma unroll
;     for (int i = 0; i < 16; ++i) { oA0[i] = 0.f; oA1[i] = 0.f; oB0[i] = 0.f; oB1[i] = 0.f; }
;     float mA = -40.0f, lA = 0.f, mB = -40.0f, lB = 0.f;
;     constexpr int NB = 11;
;     bf16x8s kf[4]; u32x4a vg[4];
;     attn_loadk<NatPol>(kbase, pA, 0, r, hh, kf);
;     attn_loadv<NatPol>(vbase, pA, 0, r, hh, vg);
.LBB0_386:
	s_or_b64 exec, exec, s[6:7]
	s_and_b32 s1, s52, 56
	v_add_u32_e32 v0, s1, v176
	s_ashr_i32 s1, s52, 10
	s_lshl_b32 s6, s1, 4
	v_and_b32_e32 v0, -4, v0
	s_or_b32 s6, s6, s0
	v_med3_i32 v1, v0, 4, 60
	v_sub_u32_e32 v2, 0, v177
	v_or_b32_e32 v4, v0, v177
	s_ashr_i32 s7, s6, 31
	v_add_u32_e32 v2, v2, v1
	v_or_b32_e32 v6, 2, v4
	v_lshl_or_b32 v205, v4, 6, v178
	s_lshl_b64 s[6:7], s[6:7], 19
	v_readlane_b32 s14, v252, 36
	v_sub_u32_e32 v206, v2, v0
	v_min_i32_e32 v0, 60, v4
	v_lshl_or_b32 v204, v6, 6, v178
	v_readlane_b32 s15, v252, 37
	s_add_u32 s6, s14, s6
	v_lshlrev_b32_e32 v168, 6, v205
	v_add_u32_e32 v5, -4, v0
	v_min_i32_e32 v0, 60, v6
	s_addc_u32 s7, s15, s7
	v_ashrrev_i32_e32 v169, 31, v168
	v_lshlrev_b32_e32 v166, 6, v204
	v_add_u32_e32 v165, -4, v1
	v_add_u32_e32 v207, -4, v1
	v_add_u32_e32 v7, -4, v0
	v_lshl_add_u64 v[0:1], v[168:169], 1, s[6:7]
	v_ashrrev_i32_e32 v167, 31, v166
	v_lshl_add_u64 v[0:1], v[0:1], 0, v[192:193]
	v_lshl_add_u64 v[2:3], v[166:167], 1, s[6:7]
	s_waitcnt lgkmcnt(0)
	s_cmp_eq_u32 s100, 1
	s_cbranch_scc1 .Lnat0_nobar2
	s_barrier
.Lnat0_nobar2:
	s_add_u32 s14, s6, 0x4000000
	v_lshl_add_u64 v[2:3], v[2:3], 0, v[192:193]
	global_load_dwordx4 v[96:99], v[0:1], off
	global_load_dwordx4 v[100:103], v[0:1], off offset:32
	global_load_dwordx4 v[104:107], v[2:3], off
	global_load_dwordx4 v[108:111], v[2:3], off offset:32
	global_load_dwordx4 v[112:115], v[0:1], off offset:64
	global_load_dwordx4 v[116:119], v[0:1], off offset:96
	global_load_dwordx4 v[120:123], v[2:3], off offset:64
	global_load_dwordx4 v[124:127], v[2:3], off offset:96
	v_lshlrev_b32_e32 v211, 12, v207
	s_addc_u32 s15, s7, 0
	v_add_lshl_u32 v0, v211, v181, 1
	v_mov_b32_e32 v1, v193
	v_lshl_add_u64 v[0:1], s[14:15], 0, v[0:1]
	v_lshl_add_u64 v[0:1], v[0:1], 0, v[192:193]
	v_cmp_lt_i32_e32 vcc, 3, v4
	v_mov_b32_e32 v163, v193
	v_lshl_add_u64 v[0:1], s[6:7], 0, v[162:163]
	v_cndmask_b32_e32 v208, 0, v5, vcc
	v_cmp_lt_i32_e32 vcc, 3, v6
	s_mov_b64 s[18:19], 0x8000000
	v_lshl_add_u64 v[170:171], v[0:1], 0, s[18:19]
	s_mov_b64 s[18:19], 0x4000000
	v_lshl_add_u64 v[240:241], v[0:1], 0, s[18:19]
	v_lshrrev_b32_e32 v242, 6, v195
	v_mul_u32_u24_e32 v242, 0x1200, v242
	v_and_b32_e32 v243, 31, v195
	v_mul_u32_u24_e32 v243, 0x90, v243
	v_add_u32_e32 v242, v242, v243
	v_bfe_u32 v243, v195, 5, 1
	v_lshl_add_u32 v242, v243, 4, v242
	v_add_u32_e32 v242, 0x9000, v242
	v_add_u32_e32 v243, 0x9000, v190
	v_add_u32_e32 v200, v211, v182
	v_or_b32_e32 v202, v211, v183
	v_ashrrev_i32_e32 v201, 31, v200
	v_ashrrev_i32_e32 v203, 31, v202
	v_lshl_add_u64 v[200:201], v[200:201], 1, v[240:241]
	v_lshl_add_u64 v[202:203], v[202:203], 1, v[240:241]
	global_load_dwordx4 v[140:143], v[200:201], off
	global_load_dwordx4 v[136:139], v[202:203], off
	v_add_u32_e32 v200, v211, v184
	v_add_u32_e32 v202, v211, v185
	v_ashrrev_i32_e32 v201, 31, v200
	v_ashrrev_i32_e32 v203, 31, v202
	v_lshl_add_u64 v[200:201], v[200:201], 1, v[240:241]
	v_lshl_add_u64 v[202:203], v[202:203], 1, v[240:241]
	global_load_dwordx4 v[132:135], v[200:201], off
	global_load_dwordx4 v[128:131], v[202:203], off
	v_add_u32_e32 v200, v211, v182
	v_or_b32_e32 v202, v211, v183
	v_ashrrev_i32_e32 v201, 31, v200
	v_ashrrev_i32_e32 v203, 31, v202
	v_lshl_add_u64 v[200:201], v[200:201], 1, v[170:171]
	v_lshl_add_u64 v[202:203], v[202:203], 1, v[170:171]
	global_load_dwordx4 v[144:147], v[200:201], off
	global_load_dwordx4 v[148:151], v[202:203], off
	v_add_u32_e32 v200, v211, v184
	v_add_u32_e32 v202, v211, v185
	v_ashrrev_i32_e32 v201, 31, v200
	v_ashrrev_i32_e32 v203, 31, v202
	v_lshl_add_u64 v[200:201], v[200:201], 1, v[170:171]
	v_lshl_add_u64 v[202:203], v[202:203], 1, v[170:171]
	global_load_dwordx4 v[152:155], v[200:201], off
	global_load_dwordx4 v[156:159], v[202:203], off
	v_cndmask_b32_e32 v209, 0, v7, vcc
	v_mov_b32_e32 v0, 0
	s_mov_b32 s10, -4
	s_mov_b32 s11, 0
	v_lshl_add_u64 v[172:173], s[14:15], 0, v[192:193]
	v_add_u32_e32 v163, 8, v208
	v_add_u32_e32 v210, 8, v209
	v_mov_b32_e32 v212, 0xc2200000
	v_mov_b32_e32 v213, 0xc2200000
	v_mov_b32_e32 v1, v0
	v_mov_b32_e32 v2, v0
	v_mov_b32_e32 v3, v0
	v_mov_b32_e32 v4, v0
	v_mov_b32_e32 v5, v0
	v_mov_b32_e32 v6, v0
	v_mov_b32_e32 v7, v0
	v_mov_b32_e32 v8, v0
	v_mov_b32_e32 v9, v0
	v_mov_b32_e32 v10, v0
	v_mov_b32_e32 v11, v0
	v_mov_b32_e32 v12, v0
	v_mov_b32_e32 v13, v0
	v_mov_b32_e32 v14, v0
	v_mov_b32_e32 v15, v0
	v_mov_b32_e32 v16, v0
	v_mov_b32_e32 v17, v0
	v_mov_b32_e32 v18, v0
	v_mov_b32_e32 v19, v0
	v_mov_b32_e32 v20, v0
	v_mov_b32_e32 v21, v0
	v_mov_b32_e32 v22, v0
	v_mov_b32_e32 v23, v0
	v_mov_b32_e32 v24, v0
	v_mov_b32_e32 v25, v0
	v_mov_b32_e32 v26, v0
	v_mov_b32_e32 v27, v0
	v_mov_b32_e32 v28, v0
	v_mov_b32_e32 v29, v0
	v_mov_b32_e32 v30, v0
	v_mov_b32_e32 v31, v0
	v_mov_b32_e32 v32, v0
	v_mov_b32_e32 v33, v0
	v_mov_b32_e32 v34, v0
	v_mov_b32_e32 v35, v0
	v_mov_b32_e32 v36, v0
	v_mov_b32_e32 v37, v0
	v_mov_b32_e32 v38, v0
	v_mov_b32_e32 v39, v0
	v_mov_b32_e32 v40, v0
	v_mov_b32_e32 v41, v0
	v_mov_b32_e32 v42, v0
	v_mov_b32_e32 v43, v0
	v_mov_b32_e32 v44, v0
	v_mov_b32_e32 v45, v0
	v_mov_b32_e32 v46, v0
	v_mov_b32_e32 v47, v0
	v_mov_b32_e32 v48, v0
	v_mov_b32_e32 v49, v0
	v_mov_b32_e32 v50, v0
	v_mov_b32_e32 v51, v0
	v_mov_b32_e32 v52, v0
	v_mov_b32_e32 v53, v0
	v_mov_b32_e32 v54, v0
	v_mov_b32_e32 v55, v0
	v_mov_b32_e32 v56, v0
	v_mov_b32_e32 v57, v0
	v_mov_b32_e32 v58, v0
	v_mov_b32_e32 v59, v0
	v_mov_b32_e32 v60, v0
	v_mov_b32_e32 v61, v0
	v_mov_b32_e32 v62, v0
	v_mov_b32_e32 v63, v0
	v_mov_b32_e32 v174, v0
	v_mov_b32_e32 v175, v0
	s_branch .LBB0_388

; #define LAS __attribute__((address_space(3)))
; __device__ __forceinline__ int otid() { int t = threadIdx.x; asm volatile("" : "+v"(t)); return t; }
;     __device__ __forceinline__ void init(int n, int hh) { rq = r0 + (n >> 4); const int cq = c0 + (n & 15); rsq = rq - 4; rsq = rsq < 0 ? 0 : (rsq > 56 ? 56 : rsq); int csq = cq - 8; csq = csq < 0 ? 0 : (csq > 48 ? 48 : csq);
;         cbase = cw0 + 4 * hh - cq + 15; int m = 0;
; #pragma unroll
;         for (int i = 0; i < 16; ++i) { const int ck = cw0 + 4 * hh + CI32(i); m |= (ck >= csq && ck < csq + 16) ? (1 << i) : 0; }
;         colmask = m; }
; __device__ void ph_natten_mfma(const Params& P, int j, int half, const bf16_t* __restrict__ proj, bf16_t* __restrict__ yout, unsigned char* lds_raw) {
;     const int tid = otid(); const int lane = tid & 63, wid = tid >> 6;
;     LAS float* tbl = (LAS float*)lds_raw; LAS unsigned char* wl = (LAS unsigned char*)lds_raw + 32768 + wid * 4608;
;     const float* rpb = P.in[18] + (size_t)j * 32 * 15 * 31;
;     const int G = gridDim.x, bid = blockIdx.x, vb = (G % 8 == 0) ? (bid & 7) * (G >> 3) + (bid >> 3) : bid;
; #pragma unroll 1
;     for (int id0 = vb * 8; id0 < 8192; id0 += G * 8) {
;         const int p = id0 >> 6, b = p >> 4, h = p & 15, wt = (id0 & 63) + wid;
;         __syncthreads();
;         for (int x = tid; x < 465; x += NT) tbl[64 + x] = rpb[(size_t)(half * 16 + h) * 465 + x] * 1.44269504088896341f;
;         __syncthreads();
;         const int r0 = (wt >> 2) * 4, c0 = (wt & 3) * 16;
;         int rs0 = r0 - 4; rs0 = rs0 < 0 ? 0 : (rs0 > 56 ? 56 : rs0); int cw0 = c0 - 8; cw0 = cw0 < 0 ? 0 : (cw0 > 32 ? 32 : cw0);
;         NatPol polA{r0, c0, rs0, cw0, tbl + 64, 0, 0, 0, 0}, polB{r0 + 2, c0, rs0, cw0, tbl + 64, 0, 0, 0, 0};
.LBB0_557:
	s_andn2_b64 vcc, exec, s[6:7]
	s_cbranch_vccnz .LBB0_671
	v_readlane_b32 s0, v255, 47
	v_readlane_b32 s1, v255, 48
	s_and_b64 vcc, exec, s[0:1]
	v_readlane_b32 s0, v254, 25
	v_readlane_b32 s1, v254, 26
	s_mov_b64 s[6:7], -1
	s_waitcnt vmcnt(0)
	v_cndmask_b32_e64 v0, 0, 1, s[0:1]
	v_cmp_ne_u32_e64 s[38:39], 1, v0
	s_cbranch_vccz .LBB0_577
	v_mov_b32_e32 v160, v195
	s_and_b64 vcc, exec, s[38:39]
	s_cbranch_vccnz .LBB0_576
	v_readlane_b32 s0, v255, 50
	v_ashrrev_i32_e32 v176, 6, v160
	s_mul_i32 s0, s0, 0xe880
	s_add_u32 s12, s68, s0
	s_movk_i32 s0, 0x1200
	v_lshlrev_b32_e32 v2, 4, v176
	v_mul_lo_u32 v0, v176, s0
	v_and_b32_e32 v2, 48, v2
	v_add_u32_e32 v1, 0, v0
	v_and_b32_e32 v0, 63, v160
	v_med3_u32 v3, v2, 8, 40
	v_bfe_u32 v7, v160, 5, 1
	v_and_or_b32 v178, v160, 15, v2
	v_add_u32_e32 v5, -8, v3
	v_lshlrev_b32_e32 v4, 2, v0
	v_med3_u32 v2, v178, 8, 56
	v_lshlrev_b32_e32 v0, 2, v7
	v_add_u32_e32 v8, -8, v2
	v_or_b32_e32 v9, v5, v0
	v_add_u32_e32 v10, 8, v2
	v_readlane_b32 s1, v255, 51
	s_movk_i32 s0, 0x1d1
	v_cmp_ge_u32_e32 vcc, v9, v8
	v_cmp_lt_u32_e64 s[42:43], v9, v10
	v_or_b32_e32 v11, 1, v9
	s_addc_u32 s17, s69, 0
	v_cmp_gt_i32_e64 s[40:41], s0, v160
	s_and_b64 s[0:1], vcc, s[42:43]
	v_cmp_ge_u32_e32 vcc, v11, v8
	v_cmp_lt_u32_e64 s[42:43], v11, v10
	v_or_b32_e32 v12, 2, v9
	s_and_b64 s[6:7], vcc, s[42:43]
	v_cmp_ge_u32_e32 vcc, v12, v8
	v_cmp_lt_u32_e64 s[42:43], v12, v10
	v_or_b32_e32 v13, 3, v9
	v_cndmask_b32_e64 v11, 0, 2, s[6:7]
	s_and_b64 s[6:7], vcc, s[42:43]
	v_cmp_ge_u32_e32 vcc, v13, v8
	v_cmp_lt_u32_e64 s[42:43], v13, v10
	v_add_u32_e32 v14, 8, v9
	v_cndmask_b32_e64 v12, 0, 4, s[6:7]
	s_and_b64 s[6:7], vcc, s[42:43]
	v_cmp_ge_u32_e32 vcc, v14, v8
	v_cmp_lt_u32_e64 s[42:43], v9, v2
	v_add_u32_e32 v2, 9, v9
	v_cndmask_b32_e64 v13, 0, 8, s[6:7]
	s_and_b64 s[6:7], s[42:43], vcc
	v_cmp_ge_u32_e32 vcc, v2, v8
	v_cmp_lt_u32_e64 s[42:43], v2, v10
	v_add_u32_e32 v2, 10, v9
	v_cndmask_b32_e64 v14, 0, 16, s[6:7]
	s_and_b64 s[6:7], vcc, s[42:43]
	v_cmp_ge_u32_e32 vcc, v2, v8
	v_cmp_lt_u32_e64 s[42:43], v2, v10
	v_add_u32_e32 v2, 11, v9
	v_cndmask_b32_e64 v15, 0, 32, s[6:7]
	s_and_b64 s[6:7], vcc, s[42:43]
	v_cmp_ge_u32_e32 vcc, v2, v8
	v_cmp_lt_u32_e64 s[42:43], v2, v10
	s_and_b64 vcc, vcc, s[42:43]
	v_mov_b32_e32 v2, 0x80
	v_cndmask_b32_e32 v17, 0, v2, vcc
	v_add_u32_e32 v2, 16, v9
	v_cmp_ge_u32_e32 vcc, v2, v8
	v_cmp_lt_u32_e64 s[42:43], v2, v10
	s_and_b64 vcc, vcc, s[42:43]
	v_mov_b32_e32 v2, 0x100
	v_cndmask_b32_e32 v18, 0, v2, vcc
	v_add_u32_e32 v2, 17, v9
	v_cmp_ge_u32_e32 vcc, v2, v8
	v_cmp_lt_u32_e64 s[42:43], v2, v10
	s_and_b64 vcc, vcc, s[42:43]
	v_mov_b32_e32 v2, 0x200
	v_cndmask_b32_e32 v19, 0, v2, vcc
	v_add_u32_e32 v2, 18, v9
	v_cmp_ge_u32_e32 vcc, v2, v8
	v_cmp_lt_u32_e64 s[42:43], v2, v10
	s_and_b64 vcc, vcc, s[42:43]
	v_mov_b32_e32 v2, 0x400
	v_cndmask_b32_e32 v20, 0, v2, vcc
	v_add_u32_e32 v2, 19, v9
	v_cmp_ge_u32_e32 vcc, v2, v8
	v_cmp_lt_u32_e64 s[42:43], v2, v10
	s_and_b64 vcc, vcc, s[42:43]
	v_mov_b32_e32 v2, 0x800
	v_cndmask_b32_e32 v21, 0, v2, vcc
	v_add_u32_e32 v2, 24, v9
	v_cmp_ge_u32_e32 vcc, v2, v8
	v_cmp_lt_u32_e64 s[42:43], v2, v10
	s_and_b64 vcc, vcc, s[42:43]
	v_add_u32_e32 v2, 25, v9
	v_cndmask_b32_e32 v22, 0, v231, vcc
	v_cmp_ge_u32_e32 vcc, v2, v8
	v_cmp_lt_u32_e64 s[42:43], v2, v10
	s_and_b64 vcc, vcc, s[42:43]
	v_add_u32_e32 v2, 26, v9
	v_cndmask_b32_e32 v23, 0, v238, vcc
	v_cmp_ge_u32_e32 vcc, v2, v8
	v_cmp_lt_u32_e64 s[42:43], v2, v10
	v_add_u32_e32 v2, 27, v9
	v_cndmask_b32_e64 v9, 0, 1, s[0:1]
	v_or_b32_e32 v9, v11, v9
	v_or3_b32 v9, v9, v12, v13
	v_cndmask_b32_e64 v16, 0, 64, s[6:7]
	v_or3_b32 v9, v9, v14, v15
	s_and_b64 vcc, vcc, s[42:43]
	v_or3_b32 v9, v9, v16, v17
	v_cndmask_b32_e32 v24, 0, v230, vcc
	v_cmp_ge_u32_e32 vcc, v2, v8
	v_cmp_lt_u32_e64 s[42:43], v2, v10
	v_or3_b32 v9, v9, v18, v19
	s_and_b64 vcc, vcc, s[42:43]
	v_mov_b32_e32 v2, 0x8000
	v_or3_b32 v9, v9, v20, v21
	v_cndmask_b32_e32 v8, 0, v2, vcc
	v_or3_b32 v9, v9, v22, v23
	v_and_b32_e32 v6, 31, v160
	v_or3_b32 v179, v9, v24, v8
	v_bfe_u32 v8, v160, 3, 3
	v_add_lshl_u32 v181, v5, v6, 6
	v_or_b32_e32 v5, v5, v8
	v_lshlrev_b32_e32 v182, 6, v5
	v_or_b32_e32 v5, v3, v8
	v_lshlrev_b32_e32 v183, 6, v5
	v_lshlrev_b32_e32 v5, 4, v160
	v_and_b32_e32 v5, 0x70, v5
	s_movk_i32 s0, 0x240
	v_lshlrev_b32_e32 v2, 3, v7
	v_add_u32_e32 v5, v1, v5
	v_mad_u32_u24 v1, v7, s0, v1
	v_mul_u32_u24_e32 v7, 0x90, v8
	v_max_i32_e32 v8, 0xffffffd1, v160
	v_sub_u32_e32 v8, v8, v160
	v_add_u32_e32 v8, 0x1ff, v8
	v_lshrrev_b32_e32 v9, 9, v8
	v_xor_b32_e32 v180, 0x80, v4
	v_lshlrev_b32_e32 v4, 3, v160
	v_add_u32_e32 v9, 1, v9
	v_or_b32_e32 v3, v3, v0
	s_add_i32 s35, 0, 0x100
	v_readlane_b32 s0, v255, 16
	v_readlane_b32 s1, v255, 56
	v_and_b32_e32 v4, 56, v4
	v_lshlrev_b32_e32 v6, 1, v6
	v_and_b32_e32 v186, 0xfffffe, v9
	v_sub_u32_e32 v3, v3, v178
	s_add_u32 s50, s0, s1
	v_readlane_b32 s0, v255, 17
	v_bfe_u32 v177, v160, 4, 1
	v_add_u32_e32 v184, 0x200, v183
	v_add_u32_e32 v185, 0x400, v183
	v_cmp_lt_u32_e64 s[42:43], s82, v8
	v_lshl_add_u32 v187, v186, 9, v160
	v_add_u32_e32 v161, 0x200, v160
	v_cmp_ne_u32_e64 s[44:45], v9, v186
	v_lshl_add_u32 v188, v3, 2, 0
	v_lshlrev_b32_e32 v189, 2, v160
	s_addc_u32 s51, s0, s93
	v_lshlrev_b32_e32 v192, 1, v2
	v_lshlrev_b32_e32 v162, 1, v4
	v_add_u32_e32 v190, v5, v7
	v_add_u32_e32 v191, v1, v6
	v_lshlrev_b32_e32 v164, 1, v0
	v_readlane_b32 s52, v254, 29
	v_lshrrev_b32_e32 v191, 6, v195
	v_mul_u32_u24_e32 v191, 0x1200, v191
	v_bfe_u32 v198, v195, 5, 1
	v_mul_u32_u24_e32 v198, 0x240, v198
	v_add_u32_e32 v191, v191, v198
	v_bfe_u32 v198, v195, 2, 2
	v_mul_u32_u24_e32 v198, 0x90, v198
	v_add_u32_e32 v191, v191, v198
	v_bfe_u32 v198, v195, 4, 1
	v_lshl_add_u32 v191, v198, 5, v191
	v_and_b32_e32 v198, 3, v195
	v_lshl_add_u32 v191, v198, 3, v191
	s_mov_b32 s101, -1
	s_branch .LBB0_562

; __device__ void ph_natten_mfma(const Params& P, int j, int half, const bf16_t* __restrict__ proj, bf16_t* __restrict__ yout, unsigned char* lds_raw) {
;     ...
;     for (int id0 = vb * 8; id0 < 8192; id0 += G * 8) {
;         const int p = id0 >> 6, b = p >> 4, h = p & 15, wt = (id0 & 63) + wid;
;         __syncthreads();
;         for (int x = tid; x < 465; x += NT) tbl[64 + x] = rpb[(size_t)(half * 16 + h) * 465 + x] * 1.44269504088896341f;
;         __syncthreads();
.LBB0_562:
	s_bfe_u32 s0, s52, 0x40006
	s_mov_b32 s100, 1
	s_mov_b64 s[6:7], exec
	s_cmp_eq_u32 s0, s101
	s_cbranch_scc1 .LBB0_572
	s_mov_b32 s100, 0
	s_mov_b32 s101, s0
	s_barrier
	s_and_saveexec_b64 s[6:7], s[40:41]
	s_cbranch_execz .LBB0_572
	s_mov_b64 s[14:15], -1
	v_mov_b32_e32 v0, v160
	v_mov_b32_e32 v1, v189
	s_and_saveexec_b64 s[10:11], s[42:43]
	s_cbranch_execz .LBB0_569
	s_mul_i32 s1, s0, 0x744
	s_add_u32 s1, s12, s1
	s_addc_u32 s15, s17, 0
	s_add_u32 s14, s1, 0x7440
	s_addc_u32 s15, s15, 0
	s_mov_b64 s[30:31], 0
	v_mov_b32_e32 v2, v186
	v_add_u32_e32 v3, s35, v189
	v_mov_b64_e32 v[0:1], v[160:161]
